# v4 + K-GEMM epilogue rope loop unrolled (16 loads in flight instead of 4 serial load-wait-store trips)
# speedup vs baseline: 1.0063x; 1.0063x over previous
.LBB0_671:
	s_or_b64 exec, exec, s[8:9]
	s_lshl_b32 s53, s14, 8
	v_ashrrev_i32_e32 v129, 1, v166
	v_add_u32_e32 v154, s53, v129
	v_ashrrev_i32_e32 v155, 31, v154
	s_waitcnt lgkmcnt(0)
	s_barrier
	s_waitcnt lgkmcnt(0)
	v_lshl_add_u64 v[130:131], v[154:155], 2, s[66:67]
	global_load_dword v134, v[130:131], off
	v_lshl_add_u32 v129, v166, 4, 0
	v_add_u32_e32 v129, 0x20400, v129
	ds_read_b128 v[130:133], v129
	v_lshl_add_u32 v156, v128, 3, s95
	s_mov_b32 s8, 0x800000
	v_lshl_add_u32 v135, v166, 2, 0
	v_add_u32_e32 v167, 0x22400, v135
	s_waitcnt lgkmcnt(0)
	v_mov_b32_e32 v128, v131
	v_mov_b32_e32 v129, v132
	v_mov_b32_e32 v131, v133
	v_pk_add_f32 v[128:129], v[128:129], v[130:131]
	v_ashrrev_i32_e32 v157, 31, v156
	v_add_f32_e32 v128, v128, v129
	v_lshl_add_u64 v[132:133], v[156:157], 2, s[20:21]
	v_add_u32_e32 v168, s94, v144
	v_add_u32_e32 v170, s53, v168
	s_waitcnt vmcnt(0)
	v_add_f32_e32 v128, v134, v128
	v_fmamk_f32 v128, v128, 0x3baaaaab, v165
	v_mul_f32_e32 v129, 0x4b800000, v128
	v_cmp_gt_f32_e32 vcc, s8, v128
	s_nop 1
	v_cndmask_b32_e32 v128, v128, v129, vcc
	v_rsq_f32_e32 v128, v128
	s_nop 0
	v_mul_f32_e32 v129, 0x45800000, v128
	v_cndmask_b32_e32 v128, v128, v129, vcc
	ds_write_b32 v167, v128
	s_waitcnt lgkmcnt(0)
	s_barrier
	global_load_dwordx4 v[128:131], v[132:133], off offset:16
	s_nop 0
	global_load_dwordx4 v[132:135], v[132:133], off
	v_cmp_lt_i32_e32 vcc, s55, v170
	s_and_saveexec_b64 s[8:9], vcc
	s_xor_b64 s[8:9], exec, s[8:9]
	v_add_u32_e32 v144, 0xffffc000, v170
	v_lshrrev_b32_e32 v169, 8, v144
	v_and_b32_e32 v144, 0xff, v168
	s_andn2_saveexec_b64 s[8:9], s[8:9]
	v_and_b32_e32 v144, 0x1fff, v170
	v_ashrrev_i32_e32 v169, 13, v170
	v_add_u32_e32 v144, 0x100, v144
	s_or_b64 exec, exec, s[8:9]
	v_lshl_add_u32 v170, v168, 3, 0
	v_add_u32_e32 v170, 0x22400, v170
	ds_read_b64 v[170:171], v170
	s_waitcnt vmcnt(0)
	v_pk_mul_f32 v[124:125], v[124:125], v[132:133]
	v_pk_mul_f32 v[120:121], v[120:121], v[128:129]
	v_mov_b32_e32 v174, v145
	v_mov_b32_e32 v175, v145
	s_waitcnt lgkmcnt(0)
	v_pk_mul_f32 v[124:125], v[124:125], v[170:171] op_sel_hi:[1,0]
	v_pk_mul_f32 v[120:121], v[120:121], v[170:171] op_sel_hi:[1,0]
	v_cvt_pk_fp8_f32 v174, v124, v125
	v_cvt_pk_fp8_f32 v175, v120, v121
	s_lshl_b32 s14, s15, 1
	v_pk_mul_f32 v[126:127], v[126:127], v[134:135]
	v_pk_mul_f32 v[120:121], v[122:123], v[130:131]
	v_lshl_add_u32 v169, v169, 3, s14
	v_pk_mul_f32 v[126:127], v[126:127], v[170:171] op_sel_hi:[1,0]
	v_pk_mul_f32 v[120:121], v[120:121], v[170:171] op_sel_hi:[1,0]
	v_pk_mul_f32 v[116:117], v[116:117], v[132:133]
	v_pk_mul_f32 v[112:113], v[112:113], v[128:129]
	v_mad_i64_i32 v[172:173], s[8:9], v169, s46, v[144:145]
	v_cvt_pk_fp8_f32 v174, v126, v127 op_sel:[0,0,1]
	v_cvt_pk_fp8_f32 v175, v120, v121 op_sel:[0,0,1]
	v_mov_b64_e32 v[120:121], s[56:57]
	v_pk_mul_f32 v[116:117], v[116:117], v[170:171] op_sel:[0,1]
	v_pk_mul_f32 v[112:113], v[112:113], v[170:171] op_sel:[0,1]
	v_mov_b32_e32 v124, v145
	v_mov_b32_e32 v125, v145
	v_mad_u64_u32 v[122:123], s[8:9], v172, s79, v[120:121]
	v_cvt_pk_fp8_f32 v124, v116, v117
	v_cvt_pk_fp8_f32 v125, v112, v113
	v_mad_i32_i24 v123, v173, s79, v123
	v_lshl_add_u64 v[122:123], v[122:123], 0, v[156:157]
	v_pk_mul_f32 v[118:119], v[118:119], v[134:135]
	v_pk_mul_f32 v[112:113], v[114:115], v[130:131]
	global_store_dwordx2 v[122:123], v[174:175], off
	v_or_b32_e32 v122, 1, v169
	v_pk_mul_f32 v[118:119], v[118:119], v[170:171] op_sel:[0,1]
	v_pk_mul_f32 v[112:113], v[112:113], v[170:171] op_sel:[0,1]
	v_mad_i64_i32 v[122:123], s[8:9], v122, s46, v[144:145]
	v_cvt_pk_fp8_f32 v124, v118, v119 op_sel:[0,0,1]
	v_cvt_pk_fp8_f32 v125, v112, v113 op_sel:[0,0,1]
	v_mad_u64_u32 v[112:113], s[8:9], v122, s79, v[120:121]
	v_mad_i32_i24 v113, v123, s79, v113
	v_lshl_add_u64 v[112:113], v[112:113], 0, v[156:157]
	global_store_dwordx2 v[112:113], v[124:125], off
	v_add_u32_e32 v112, 16, v168
	v_add_u32_e32 v114, s53, v112
	v_cmp_lt_i32_e32 vcc, s55, v114
	s_and_saveexec_b64 s[8:9], vcc
	s_xor_b64 s[8:9], exec, s[8:9]
	v_add_u32_e32 v113, 0xffffc000, v114
	v_lshrrev_b32_e32 v113, 8, v113
	v_and_b32_e32 v144, 0xff, v112
	s_andn2_saveexec_b64 s[8:9], s[8:9]
	v_ashrrev_i32_e32 v113, 13, v114
	v_and_b32_e32 v114, 0x1fff, v114
	v_add_u32_e32 v144, 0x100, v114
	s_or_b64 exec, exec, s[8:9]
	v_lshl_add_u32 v112, v112, 3, 0
	v_add_u32_e32 v112, 0x22400, v112
	v_lshl_add_u32 v118, v113, 3, s14
	ds_read_b64 v[112:113], v112
	v_pk_mul_f32 v[108:109], v[108:109], v[132:133]
	v_pk_mul_f32 v[104:105], v[104:105], v[128:129]
	v_mov_b32_e32 v116, v145
	v_mov_b32_e32 v117, v145
	s_waitcnt lgkmcnt(0)
	v_pk_mul_f32 v[108:109], v[108:109], v[112:113] op_sel_hi:[1,0]
	v_pk_mul_f32 v[104:105], v[104:105], v[112:113] op_sel_hi:[1,0]
	v_cvt_pk_fp8_f32 v116, v108, v109
	v_cvt_pk_fp8_f32 v117, v104, v105
	v_pk_mul_f32 v[110:111], v[110:111], v[134:135]
	v_pk_mul_f32 v[104:105], v[106:107], v[130:131]
	v_pk_mul_f32 v[110:111], v[110:111], v[112:113] op_sel_hi:[1,0]
	v_pk_mul_f32 v[104:105], v[104:105], v[112:113] op_sel_hi:[1,0]
	v_pk_mul_f32 v[100:101], v[100:101], v[132:133]
	v_pk_mul_f32 v[96:97], v[96:97], v[128:129]
	v_mad_i64_i32 v[114:115], s[8:9], v118, s46, v[144:145]
	v_cvt_pk_fp8_f32 v116, v110, v111 op_sel:[0,0,1]
	v_cvt_pk_fp8_f32 v117, v104, v105 op_sel:[0,0,1]
	v_mov_b64_e32 v[104:105], s[56:57]
	v_pk_mul_f32 v[100:101], v[100:101], v[112:113] op_sel:[0,1]
	v_pk_mul_f32 v[96:97], v[96:97], v[112:113] op_sel:[0,1]
	v_mov_b32_e32 v108, v145
	v_mov_b32_e32 v109, v145
	v_mad_u64_u32 v[106:107], s[8:9], v114, s79, v[104:105]
	v_cvt_pk_fp8_f32 v108, v100, v101
	v_cvt_pk_fp8_f32 v109, v96, v97
	v_mad_i32_i24 v107, v115, s79, v107
	v_lshl_add_u64 v[106:107], v[106:107], 0, v[156:157]
	v_pk_mul_f32 v[102:103], v[102:103], v[134:135]
	v_pk_mul_f32 v[96:97], v[98:99], v[130:131]
	global_store_dwordx2 v[106:107], v[116:117], off
	v_or_b32_e32 v106, 1, v118
	v_pk_mul_f32 v[102:103], v[102:103], v[112:113] op_sel:[0,1]
	v_pk_mul_f32 v[96:97], v[96:97], v[112:113] op_sel:[0,1]
	v_mad_i64_i32 v[106:107], s[8:9], v106, s46, v[144:145]
	v_cvt_pk_fp8_f32 v108, v102, v103 op_sel:[0,0,1]
	v_cvt_pk_fp8_f32 v109, v96, v97 op_sel:[0,0,1]
	v_mad_u64_u32 v[96:97], s[8:9], v106, s79, v[104:105]
	v_mad_i32_i24 v97, v107, s79, v97
	v_lshl_add_u64 v[96:97], v[96:97], 0, v[156:157]
	global_store_dwordx2 v[96:97], v[108:109], off
	v_add_u32_e32 v96, 32, v168
	v_add_u32_e32 v98, s53, v96
	v_cmp_lt_i32_e32 vcc, s55, v98
	s_and_saveexec_b64 s[8:9], vcc
	s_xor_b64 s[8:9], exec, s[8:9]
	v_add_u32_e32 v97, 0xffffc000, v98
	v_lshrrev_b32_e32 v97, 8, v97
	v_and_b32_e32 v144, 0xff, v96
	s_andn2_saveexec_b64 s[8:9], s[8:9]
	v_ashrrev_i32_e32 v97, 13, v98
	v_and_b32_e32 v98, 0x1fff, v98
	v_add_u32_e32 v144, 0x100, v98
	s_or_b64 exec, exec, s[8:9]
	v_lshl_add_u32 v96, v96, 3, 0
	v_add_u32_e32 v96, 0x22400, v96
	v_lshl_add_u32 v102, v97, 3, s14
	ds_read_b64 v[96:97], v96
	v_pk_mul_f32 v[92:93], v[92:93], v[132:133]
	v_pk_mul_f32 v[88:89], v[88:89], v[128:129]
	v_mov_b32_e32 v100, v145
	v_mov_b32_e32 v101, v145
	s_waitcnt lgkmcnt(0)
	v_pk_mul_f32 v[92:93], v[92:93], v[96:97] op_sel_hi:[1,0]
	v_pk_mul_f32 v[88:89], v[88:89], v[96:97] op_sel_hi:[1,0]
	v_cvt_pk_fp8_f32 v100, v92, v93
	v_cvt_pk_fp8_f32 v101, v88, v89
	v_pk_mul_f32 v[94:95], v[94:95], v[134:135]
	v_pk_mul_f32 v[88:89], v[90:91], v[130:131]
	v_pk_mul_f32 v[94:95], v[94:95], v[96:97] op_sel_hi:[1,0]
	v_pk_mul_f32 v[88:89], v[88:89], v[96:97] op_sel_hi:[1,0]
	v_pk_mul_f32 v[84:85], v[84:85], v[132:133]
	v_pk_mul_f32 v[80:81], v[80:81], v[128:129]
	v_mad_i64_i32 v[98:99], s[8:9], v102, s46, v[144:145]
	v_cvt_pk_fp8_f32 v100, v94, v95 op_sel:[0,0,1]
	v_cvt_pk_fp8_f32 v101, v88, v89 op_sel:[0,0,1]
	v_mov_b64_e32 v[88:89], s[56:57]
	v_pk_mul_f32 v[84:85], v[84:85], v[96:97] op_sel:[0,1]
	v_pk_mul_f32 v[80:81], v[80:81], v[96:97] op_sel:[0,1]
	v_mov_b32_e32 v92, v145
	v_mov_b32_e32 v93, v145
	v_mad_u64_u32 v[90:91], s[8:9], v98, s79, v[88:89]
	v_cvt_pk_fp8_f32 v92, v84, v85
	v_cvt_pk_fp8_f32 v93, v80, v81
	v_mad_i32_i24 v91, v99, s79, v91
	v_lshl_add_u64 v[90:91], v[90:91], 0, v[156:157]
	v_pk_mul_f32 v[86:87], v[86:87], v[134:135]
	v_pk_mul_f32 v[80:81], v[82:83], v[130:131]
	global_store_dwordx2 v[90:91], v[100:101], off
	v_or_b32_e32 v90, 1, v102
	v_pk_mul_f32 v[86:87], v[86:87], v[96:97] op_sel:[0,1]
	v_pk_mul_f32 v[80:81], v[80:81], v[96:97] op_sel:[0,1]
	v_mad_i64_i32 v[90:91], s[8:9], v90, s46, v[144:145]
	v_cvt_pk_fp8_f32 v92, v86, v87 op_sel:[0,0,1]
	v_cvt_pk_fp8_f32 v93, v80, v81 op_sel:[0,0,1]
	v_mad_u64_u32 v[80:81], s[8:9], v90, s79, v[88:89]
	v_mad_i32_i24 v81, v91, s79, v81
	v_lshl_add_u64 v[80:81], v[80:81], 0, v[156:157]
	global_store_dwordx2 v[80:81], v[92:93], off
	v_add_u32_e32 v80, 48, v168
	v_add_u32_e32 v82, s53, v80
	v_cmp_lt_i32_e32 vcc, s55, v82
	s_and_saveexec_b64 s[8:9], vcc
	s_xor_b64 s[8:9], exec, s[8:9]
	v_add_u32_e32 v81, 0xffffc000, v82
	v_lshrrev_b32_e32 v81, 8, v81
	v_and_b32_e32 v144, 0xff, v80
	s_andn2_saveexec_b64 s[8:9], s[8:9]
	v_ashrrev_i32_e32 v81, 13, v82
	v_and_b32_e32 v82, 0x1fff, v82
	v_add_u32_e32 v144, 0x100, v82
	s_or_b64 exec, exec, s[8:9]
	v_lshl_add_u32 v80, v80, 3, 0
	v_add_u32_e32 v80, 0x22400, v80
	v_lshl_add_u32 v86, v81, 3, s14
	ds_read_b64 v[80:81], v80
	v_pk_mul_f32 v[76:77], v[76:77], v[132:133]
	v_pk_mul_f32 v[72:73], v[72:73], v[128:129]
	v_mov_b32_e32 v84, v145
	v_mov_b32_e32 v85, v145
	s_waitcnt lgkmcnt(0)
	v_pk_mul_f32 v[76:77], v[76:77], v[80:81] op_sel_hi:[1,0]
	v_pk_mul_f32 v[72:73], v[72:73], v[80:81] op_sel_hi:[1,0]
	v_cvt_pk_fp8_f32 v84, v76, v77
	v_cvt_pk_fp8_f32 v85, v72, v73
	v_pk_mul_f32 v[78:79], v[78:79], v[134:135]
	v_pk_mul_f32 v[72:73], v[74:75], v[130:131]
	v_pk_mul_f32 v[78:79], v[78:79], v[80:81] op_sel_hi:[1,0]
	v_pk_mul_f32 v[72:73], v[72:73], v[80:81] op_sel_hi:[1,0]
	v_pk_mul_f32 v[68:69], v[68:69], v[132:133]
	v_pk_mul_f32 v[64:65], v[64:65], v[128:129]
	v_mad_i64_i32 v[82:83], s[8:9], v86, s46, v[144:145]
	v_cvt_pk_fp8_f32 v84, v78, v79 op_sel:[0,0,1]
	v_cvt_pk_fp8_f32 v85, v72, v73 op_sel:[0,0,1]
	v_mov_b64_e32 v[72:73], s[56:57]
	v_pk_mul_f32 v[68:69], v[68:69], v[80:81] op_sel:[0,1]
	v_pk_mul_f32 v[64:65], v[64:65], v[80:81] op_sel:[0,1]
	v_mov_b32_e32 v76, v145
	v_mov_b32_e32 v77, v145
	v_mad_u64_u32 v[74:75], s[8:9], v82, s79, v[72:73]
	v_cvt_pk_fp8_f32 v76, v68, v69
	v_cvt_pk_fp8_f32 v77, v64, v65
	v_mad_i32_i24 v75, v83, s79, v75
	v_lshl_add_u64 v[74:75], v[74:75], 0, v[156:157]
	v_pk_mul_f32 v[70:71], v[70:71], v[134:135]
	v_pk_mul_f32 v[64:65], v[66:67], v[130:131]
	global_store_dwordx2 v[74:75], v[84:85], off
	v_or_b32_e32 v74, 1, v86
	v_pk_mul_f32 v[70:71], v[70:71], v[80:81] op_sel:[0,1]
	v_pk_mul_f32 v[64:65], v[64:65], v[80:81] op_sel:[0,1]
	v_mad_i64_i32 v[74:75], s[8:9], v74, s46, v[144:145]
	v_cvt_pk_fp8_f32 v76, v70, v71 op_sel:[0,0,1]
	v_cvt_pk_fp8_f32 v77, v64, v65 op_sel:[0,0,1]
	v_mad_u64_u32 v[64:65], s[8:9], v74, s79, v[72:73]
	v_mad_i32_i24 v65, v75, s79, v65
	v_lshl_add_u64 v[64:65], v[64:65], 0, v[156:157]
	global_store_dwordx2 v[64:65], v[76:77], off
	v_add_u32_e32 v64, 0x80, v168
	v_add_u32_e32 v66, s53, v64
	v_cmp_lt_i32_e32 vcc, s55, v66
	s_and_saveexec_b64 s[8:9], vcc
	s_xor_b64 s[8:9], exec, s[8:9]
	v_add_u32_e32 v65, 0xffffc000, v66
	v_lshrrev_b32_e32 v65, 8, v65
	v_and_b32_e32 v144, 0xff, v64
	s_andn2_saveexec_b64 s[8:9], s[8:9]
	v_ashrrev_i32_e32 v65, 13, v66
	v_and_b32_e32 v66, 0x1fff, v66
	v_add_u32_e32 v144, 0x100, v66
	s_or_b64 exec, exec, s[8:9]
	v_lshl_add_u32 v64, v64, 3, 0
	v_add_u32_e32 v64, 0x22400, v64
	v_lshl_add_u32 v70, v65, 3, s14
	ds_read_b64 v[64:65], v64
	v_pk_mul_f32 v[60:61], v[60:61], v[132:133]
	v_pk_mul_f32 v[56:57], v[56:57], v[128:129]
	v_mov_b32_e32 v68, v145
	v_mov_b32_e32 v69, v145
	s_waitcnt lgkmcnt(0)
	v_pk_mul_f32 v[60:61], v[60:61], v[64:65] op_sel_hi:[1,0]
	v_pk_mul_f32 v[56:57], v[56:57], v[64:65] op_sel_hi:[1,0]
	v_cvt_pk_fp8_f32 v68, v60, v61
	v_cvt_pk_fp8_f32 v69, v56, v57
	v_pk_mul_f32 v[62:63], v[62:63], v[134:135]
	v_pk_mul_f32 v[56:57], v[58:59], v[130:131]
	v_pk_mul_f32 v[62:63], v[62:63], v[64:65] op_sel_hi:[1,0]
	v_pk_mul_f32 v[56:57], v[56:57], v[64:65] op_sel_hi:[1,0]
	v_pk_mul_f32 v[52:53], v[52:53], v[132:133]
	v_pk_mul_f32 v[48:49], v[48:49], v[128:129]
	v_mad_i64_i32 v[66:67], s[8:9], v70, s46, v[144:145]
	v_cvt_pk_fp8_f32 v68, v62, v63 op_sel:[0,0,1]
	v_cvt_pk_fp8_f32 v69, v56, v57 op_sel:[0,0,1]
	v_mov_b64_e32 v[56:57], s[56:57]
	v_pk_mul_f32 v[52:53], v[52:53], v[64:65] op_sel:[0,1]
	v_pk_mul_f32 v[48:49], v[48:49], v[64:65] op_sel:[0,1]
	v_mov_b32_e32 v60, v145
	v_mov_b32_e32 v61, v145
	v_mad_u64_u32 v[58:59], s[8:9], v66, s79, v[56:57]
	v_cvt_pk_fp8_f32 v60, v52, v53
	v_cvt_pk_fp8_f32 v61, v48, v49
	v_mad_i32_i24 v59, v67, s79, v59
	v_lshl_add_u64 v[58:59], v[58:59], 0, v[156:157]
	v_pk_mul_f32 v[54:55], v[54:55], v[134:135]
	v_pk_mul_f32 v[48:49], v[50:51], v[130:131]
	global_store_dwordx2 v[58:59], v[68:69], off
	v_or_b32_e32 v58, 1, v70
	v_pk_mul_f32 v[54:55], v[54:55], v[64:65] op_sel:[0,1]
	v_pk_mul_f32 v[48:49], v[48:49], v[64:65] op_sel:[0,1]
	v_mad_i64_i32 v[58:59], s[8:9], v58, s46, v[144:145]
	v_cvt_pk_fp8_f32 v60, v54, v55 op_sel:[0,0,1]
	v_cvt_pk_fp8_f32 v61, v48, v49 op_sel:[0,0,1]
	v_mad_u64_u32 v[48:49], s[8:9], v58, s79, v[56:57]
	v_mad_i32_i24 v49, v59, s79, v49
	v_lshl_add_u64 v[48:49], v[48:49], 0, v[156:157]
	global_store_dwordx2 v[48:49], v[60:61], off
	v_add_u32_e32 v48, 0x90, v168
	v_add_u32_e32 v50, s53, v48
	v_cmp_lt_i32_e32 vcc, s55, v50
	s_and_saveexec_b64 s[8:9], vcc
	s_xor_b64 s[8:9], exec, s[8:9]
	v_add_u32_e32 v49, 0xffffc000, v50
	v_lshrrev_b32_e32 v49, 8, v49
	v_and_b32_e32 v144, 0xff, v48
	s_andn2_saveexec_b64 s[8:9], s[8:9]
	v_ashrrev_i32_e32 v49, 13, v50
	v_and_b32_e32 v50, 0x1fff, v50
	v_add_u32_e32 v144, 0x100, v50
	s_or_b64 exec, exec, s[8:9]
	v_lshl_add_u32 v48, v48, 3, 0
	v_add_u32_e32 v48, 0x22400, v48
	v_lshl_add_u32 v54, v49, 3, s14
	ds_read_b64 v[48:49], v48
	v_pk_mul_f32 v[44:45], v[44:45], v[132:133]
	v_pk_mul_f32 v[40:41], v[40:41], v[128:129]
	v_mov_b32_e32 v52, v145
	v_mov_b32_e32 v53, v145
	s_waitcnt lgkmcnt(0)
	v_pk_mul_f32 v[44:45], v[44:45], v[48:49] op_sel_hi:[1,0]
	v_pk_mul_f32 v[40:41], v[40:41], v[48:49] op_sel_hi:[1,0]
	v_cvt_pk_fp8_f32 v52, v44, v45
	v_cvt_pk_fp8_f32 v53, v40, v41
	v_pk_mul_f32 v[46:47], v[46:47], v[134:135]
	v_pk_mul_f32 v[40:41], v[42:43], v[130:131]
	v_pk_mul_f32 v[46:47], v[46:47], v[48:49] op_sel_hi:[1,0]
	v_pk_mul_f32 v[40:41], v[40:41], v[48:49] op_sel_hi:[1,0]
	v_pk_mul_f32 v[36:37], v[36:37], v[132:133]
	v_pk_mul_f32 v[32:33], v[32:33], v[128:129]
	v_mad_i64_i32 v[50:51], s[8:9], v54, s46, v[144:145]
	v_cvt_pk_fp8_f32 v52, v46, v47 op_sel:[0,0,1]
	v_cvt_pk_fp8_f32 v53, v40, v41 op_sel:[0,0,1]
	v_mov_b64_e32 v[40:41], s[56:57]
	v_pk_mul_f32 v[36:37], v[36:37], v[48:49] op_sel:[0,1]
	v_pk_mul_f32 v[32:33], v[32:33], v[48:49] op_sel:[0,1]
	v_mov_b32_e32 v44, v145
	v_mov_b32_e32 v45, v145
	v_mad_u64_u32 v[42:43], s[8:9], v50, s79, v[40:41]
	v_cvt_pk_fp8_f32 v44, v36, v37
	v_cvt_pk_fp8_f32 v45, v32, v33
	v_mad_i32_i24 v43, v51, s79, v43
	v_lshl_add_u64 v[42:43], v[42:43], 0, v[156:157]
	v_pk_mul_f32 v[38:39], v[38:39], v[134:135]
	v_pk_mul_f32 v[32:33], v[34:35], v[130:131]
	global_store_dwordx2 v[42:43], v[52:53], off
	v_or_b32_e32 v42, 1, v54
	v_pk_mul_f32 v[38:39], v[38:39], v[48:49] op_sel:[0,1]
	v_pk_mul_f32 v[32:33], v[32:33], v[48:49] op_sel:[0,1]
	v_mad_i64_i32 v[42:43], s[8:9], v42, s46, v[144:145]
	v_cvt_pk_fp8_f32 v44, v38, v39 op_sel:[0,0,1]
	v_cvt_pk_fp8_f32 v45, v32, v33 op_sel:[0,0,1]
	v_mad_u64_u32 v[32:33], s[8:9], v42, s79, v[40:41]
	v_mad_i32_i24 v33, v43, s79, v33
	v_lshl_add_u64 v[32:33], v[32:33], 0, v[156:157]
	global_store_dwordx2 v[32:33], v[44:45], off
	v_add_u32_e32 v32, 0xa0, v168
	v_add_u32_e32 v34, s53, v32
	v_cmp_lt_i32_e32 vcc, s55, v34
	s_and_saveexec_b64 s[8:9], vcc
	s_xor_b64 s[8:9], exec, s[8:9]
	v_add_u32_e32 v33, 0xffffc000, v34
	v_lshrrev_b32_e32 v33, 8, v33
	v_and_b32_e32 v144, 0xff, v32
	s_andn2_saveexec_b64 s[8:9], s[8:9]
	v_ashrrev_i32_e32 v33, 13, v34
	v_and_b32_e32 v34, 0x1fff, v34
	v_add_u32_e32 v144, 0x100, v34
	s_or_b64 exec, exec, s[8:9]
	v_lshl_add_u32 v32, v32, 3, 0
	v_add_u32_e32 v32, 0x22400, v32
	v_lshl_add_u32 v38, v33, 3, s14
	ds_read_b64 v[32:33], v32
	v_pk_mul_f32 v[28:29], v[28:29], v[132:133]
	v_pk_mul_f32 v[24:25], v[24:25], v[128:129]
	v_mov_b32_e32 v36, v145
	v_mov_b32_e32 v37, v145
	s_waitcnt lgkmcnt(0)
	v_pk_mul_f32 v[28:29], v[28:29], v[32:33] op_sel_hi:[1,0]
	v_pk_mul_f32 v[24:25], v[24:25], v[32:33] op_sel_hi:[1,0]
	v_cvt_pk_fp8_f32 v36, v28, v29
	v_cvt_pk_fp8_f32 v37, v24, v25
	v_pk_mul_f32 v[30:31], v[30:31], v[134:135]
	v_pk_mul_f32 v[24:25], v[26:27], v[130:131]
	v_pk_mul_f32 v[30:31], v[30:31], v[32:33] op_sel_hi:[1,0]
	v_pk_mul_f32 v[24:25], v[24:25], v[32:33] op_sel_hi:[1,0]
	v_pk_mul_f32 v[20:21], v[20:21], v[132:133]
	v_pk_mul_f32 v[16:17], v[16:17], v[128:129]
	v_mad_i64_i32 v[34:35], s[8:9], v38, s46, v[144:145]
	v_cvt_pk_fp8_f32 v36, v30, v31 op_sel:[0,0,1]
	v_cvt_pk_fp8_f32 v37, v24, v25 op_sel:[0,0,1]
	v_mov_b64_e32 v[24:25], s[56:57]
	v_pk_mul_f32 v[20:21], v[20:21], v[32:33] op_sel:[0,1]
	v_pk_mul_f32 v[16:17], v[16:17], v[32:33] op_sel:[0,1]
	v_mov_b32_e32 v28, v145
	v_mov_b32_e32 v29, v145
	v_mad_u64_u32 v[26:27], s[8:9], v34, s79, v[24:25]
	v_cvt_pk_fp8_f32 v28, v20, v21
	v_cvt_pk_fp8_f32 v29, v16, v17
	v_mad_i32_i24 v27, v35, s79, v27
	v_lshl_add_u64 v[26:27], v[26:27], 0, v[156:157]
	v_pk_mul_f32 v[22:23], v[22:23], v[134:135]
	v_pk_mul_f32 v[16:17], v[18:19], v[130:131]
	global_store_dwordx2 v[26:27], v[36:37], off
	v_or_b32_e32 v26, 1, v38
	v_pk_mul_f32 v[22:23], v[22:23], v[32:33] op_sel:[0,1]
	v_pk_mul_f32 v[16:17], v[16:17], v[32:33] op_sel:[0,1]
	v_mad_i64_i32 v[26:27], s[8:9], v26, s46, v[144:145]
	v_cvt_pk_fp8_f32 v28, v22, v23 op_sel:[0,0,1]
	v_cvt_pk_fp8_f32 v29, v16, v17 op_sel:[0,0,1]
	v_mad_u64_u32 v[16:17], s[8:9], v26, s79, v[24:25]
	v_mad_i32_i24 v17, v27, s79, v17
	v_lshl_add_u64 v[16:17], v[16:17], 0, v[156:157]
	global_store_dwordx2 v[16:17], v[28:29], off
	v_add_u32_e32 v16, 0xb0, v168
	v_add_u32_e32 v18, s53, v16
	v_cmp_lt_i32_e32 vcc, s55, v18
	s_and_saveexec_b64 s[8:9], vcc
	s_xor_b64 s[8:9], exec, s[8:9]
	v_add_u32_e32 v17, 0xffffc000, v18
	v_lshrrev_b32_e32 v17, 8, v17
	v_and_b32_e32 v144, 0xff, v16
	s_andn2_saveexec_b64 s[8:9], s[8:9]
	v_ashrrev_i32_e32 v17, 13, v18
	v_and_b32_e32 v18, 0x1fff, v18
	v_add_u32_e32 v144, 0x100, v18
	s_or_b64 exec, exec, s[8:9]
	v_lshl_add_u32 v16, v16, 3, 0
	v_add_u32_e32 v16, 0x22400, v16
	v_lshl_add_u32 v22, v17, 3, s14
	ds_read_b64 v[16:17], v16
	v_pk_mul_f32 v[12:13], v[12:13], v[132:133]
	v_pk_mul_f32 v[8:9], v[8:9], v[128:129]
	v_mov_b32_e32 v20, v145
	v_mov_b32_e32 v21, v145
	s_waitcnt lgkmcnt(0)
	v_pk_mul_f32 v[12:13], v[12:13], v[16:17] op_sel_hi:[1,0]
	v_pk_mul_f32 v[8:9], v[8:9], v[16:17] op_sel_hi:[1,0]
	v_cvt_pk_fp8_f32 v20, v12, v13
	v_cvt_pk_fp8_f32 v21, v8, v9
	v_pk_mul_f32 v[14:15], v[14:15], v[134:135]
	v_pk_mul_f32 v[10:11], v[10:11], v[130:131]
	v_pk_mul_f32 v[14:15], v[14:15], v[16:17] op_sel_hi:[1,0]
	v_pk_mul_f32 v[10:11], v[10:11], v[16:17] op_sel_hi:[1,0]
	v_pk_mul_f32 v[4:5], v[4:5], v[132:133]
	v_pk_mul_f32 v[0:1], v[0:1], v[128:129]
	v_mad_i64_i32 v[18:19], s[8:9], v22, s46, v[144:145]
	v_cvt_pk_fp8_f32 v20, v14, v15 op_sel:[0,0,1]
	v_cvt_pk_fp8_f32 v21, v10, v11 op_sel:[0,0,1]
	v_mov_b64_e32 v[8:9], s[56:57]
	v_pk_mul_f32 v[4:5], v[4:5], v[16:17] op_sel:[0,1]
	v_pk_mul_f32 v[0:1], v[0:1], v[16:17] op_sel:[0,1]
	v_mov_b32_e32 v12, v145
	v_mov_b32_e32 v13, v145
	v_mad_u64_u32 v[10:11], s[8:9], v18, s79, v[8:9]
	v_cvt_pk_fp8_f32 v12, v4, v5
	v_cvt_pk_fp8_f32 v13, v0, v1
	v_mad_i32_i24 v11, v19, s79, v11
	v_lshl_add_u64 v[10:11], v[10:11], 0, v[156:157]
	v_pk_mul_f32 v[6:7], v[6:7], v[134:135]
	v_pk_mul_f32 v[2:3], v[2:3], v[130:131]
	global_store_dwordx2 v[10:11], v[20:21], off
	v_or_b32_e32 v10, 1, v22
	v_pk_mul_f32 v[6:7], v[6:7], v[16:17] op_sel:[0,1]
	v_pk_mul_f32 v[2:3], v[2:3], v[16:17] op_sel:[0,1]
	v_mad_i64_i32 v[10:11], s[8:9], v10, s46, v[144:145]
	v_cvt_pk_fp8_f32 v12, v6, v7 op_sel:[0,0,1]
	v_cvt_pk_fp8_f32 v13, v2, v3 op_sel:[0,0,1]
	v_mad_u64_u32 v[0:1], s[8:9], v10, s79, v[8:9]
	v_mad_i32_i24 v1, v11, s79, v1
	v_lshl_add_u64 v[0:1], v[0:1], 0, v[156:157]
	global_store_dwordx2 v[0:1], v[12:13], off
	ds_read_b32 v0, v167
	v_cmp_lt_i32_e32 vcc, s55, v154
	s_and_saveexec_b64 s[8:9], vcc
	s_xor_b64 s[8:9], exec, s[8:9]
	v_add_u32_e32 v1, 0xffffc000, v154
	v_lshrrev_b32_e32 v1, 8, v1
	v_bfe_u32 v6, v166, 1, 8
	s_andn2_saveexec_b64 s[8:9], s[8:9]
	v_and_b32_e32 v2, 0x1fff, v154
	v_ashrrev_i32_e32 v1, 13, v154
	v_add_u32_e32 v6, 0x100, v2
	s_or_b64 exec, exec, s[8:9]
	v_and_b32_e32 v7, 1, v166
	v_lshlrev_b32_e32 v8, 3, v1
	v_add3_u32 v8, v8, s14, v7
	v_mad_u64_u32 v[6:7], s[8:9], v6, s79, 0
	s_mov_b32 s8, 0x18c000
	s_nop 0
	v_mad_i64_i32 v[6:7], s[8:9], v8, s8, v[6:7]
	s_mov_b64 s[8:9], 0xaba0080
	v_lshlrev_b64 v[2:3], 8, v[154:155]
	s_waitcnt lgkmcnt(0)
	v_mov_b32_e32 v1, v0
	v_mov_b32_e32 v4, v0
	v_mov_b32_e32 v5, v0
	v_lshl_add_u64 v[6:7], v[6:7], 0, s[8:9]
	s_mov_b32 s8, 4
	v_lshl_add_u64 v[8:9], s[68:69], 0, v[2:3]
	s_mov_b64 s[14:15], 0x240000
	v_lshl_add_u64 v[8:9], v[8:9], 0, s[14:15]
	global_load_dwordx4 v[32:35], v[8:9], off
	global_load_dwordx4 v[36:39], v[8:9], off offset:16
	global_load_dwordx4 v[40:43], v[8:9], off offset:32
	global_load_dwordx4 v[44:47], v[8:9], off offset:48
	global_load_dwordx4 v[48:51], v[8:9], off offset:64
	global_load_dwordx4 v[52:55], v[8:9], off offset:80
	global_load_dwordx4 v[56:59], v[8:9], off offset:96
	global_load_dwordx4 v[60:63], v[8:9], off offset:112
	global_load_dwordx4 v[64:67], v[8:9], off offset:128
	global_load_dwordx4 v[68:71], v[8:9], off offset:144
	global_load_dwordx4 v[72:75], v[8:9], off offset:160
	global_load_dwordx4 v[76:79], v[8:9], off offset:176
	global_load_dwordx4 v[80:83], v[8:9], off offset:192
	global_load_dwordx4 v[84:87], v[8:9], off offset:208
	global_load_dwordx4 v[88:91], v[8:9], off offset:224
	global_load_dwordx4 v[92:95], v[8:9], off offset:240
	v_lshl_add_u64 v[12:13], s[68:69], 0, v[6:7]
	s_waitcnt vmcnt(12)
	v_mul_f32_e32 v32, v0, v32
	v_mul_f32_e32 v33, v0, v33
	v_mul_f32_e32 v34, v0, v34
	v_mul_f32_e32 v35, v0, v35
	v_mul_f32_e32 v36, v0, v36
	v_mul_f32_e32 v37, v0, v37
	v_mul_f32_e32 v38, v0, v38
	v_mul_f32_e32 v39, v0, v39
	v_mul_f32_e32 v40, v0, v40
	v_mul_f32_e32 v41, v0, v41
	v_mul_f32_e32 v42, v0, v42
	v_mul_f32_e32 v43, v0, v43
	v_mul_f32_e32 v44, v0, v44
	v_mul_f32_e32 v45, v0, v45
	v_mul_f32_e32 v46, v0, v46
	v_mul_f32_e32 v47, v0, v47
	v_cvt_pk_fp8_f32 v16, v32, v33
	v_cvt_pk_fp8_f32 v17, v36, v37
	v_cvt_pk_fp8_f32 v18, v40, v41
	v_cvt_pk_fp8_f32 v19, v44, v45
	v_cvt_pk_fp8_f32 v16, v34, v35 op_sel:[0,0,1]
	v_cvt_pk_fp8_f32 v17, v38, v39 op_sel:[0,0,1]
	v_cvt_pk_fp8_f32 v18, v42, v43 op_sel:[0,0,1]
	v_cvt_pk_fp8_f32 v19, v46, v47 op_sel:[0,0,1]
	global_store_dwordx4 v[12:13], v[16:19], off
	s_waitcnt vmcnt(9)
	v_mul_f32_e32 v48, v0, v48
	v_mul_f32_e32 v49, v0, v49
	v_mul_f32_e32 v50, v0, v50
	v_mul_f32_e32 v51, v0, v51
	v_mul_f32_e32 v52, v0, v52
	v_mul_f32_e32 v53, v0, v53
	v_mul_f32_e32 v54, v0, v54
	v_mul_f32_e32 v55, v0, v55
	v_mul_f32_e32 v56, v0, v56
	v_mul_f32_e32 v57, v0, v57
	v_mul_f32_e32 v58, v0, v58
	v_mul_f32_e32 v59, v0, v59
	v_mul_f32_e32 v60, v0, v60
	v_mul_f32_e32 v61, v0, v61
	v_mul_f32_e32 v62, v0, v62
	v_mul_f32_e32 v63, v0, v63
	v_cvt_pk_fp8_f32 v16, v48, v49
	v_cvt_pk_fp8_f32 v17, v52, v53
	v_cvt_pk_fp8_f32 v18, v56, v57
	v_cvt_pk_fp8_f32 v19, v60, v61
	v_cvt_pk_fp8_f32 v16, v50, v51 op_sel:[0,0,1]
	v_cvt_pk_fp8_f32 v17, v54, v55 op_sel:[0,0,1]
	v_cvt_pk_fp8_f32 v18, v58, v59 op_sel:[0,0,1]
	v_cvt_pk_fp8_f32 v19, v62, v63 op_sel:[0,0,1]
	global_store_dwordx4 v[12:13], v[16:19], off offset:16
	s_waitcnt vmcnt(6)
	v_mul_f32_e32 v64, v0, v64
	v_mul_f32_e32 v65, v0, v65
	v_mul_f32_e32 v66, v0, v66
	v_mul_f32_e32 v67, v0, v67
	v_mul_f32_e32 v68, v0, v68
	v_mul_f32_e32 v69, v0, v69
	v_mul_f32_e32 v70, v0, v70
	v_mul_f32_e32 v71, v0, v71
	v_mul_f32_e32 v72, v0, v72
	v_mul_f32_e32 v73, v0, v73
	v_mul_f32_e32 v74, v0, v74
	v_mul_f32_e32 v75, v0, v75
	v_mul_f32_e32 v76, v0, v76
	v_mul_f32_e32 v77, v0, v77
	v_mul_f32_e32 v78, v0, v78
	v_mul_f32_e32 v79, v0, v79
	v_cvt_pk_fp8_f32 v16, v64, v65
	v_cvt_pk_fp8_f32 v17, v68, v69
	v_cvt_pk_fp8_f32 v18, v72, v73
	v_cvt_pk_fp8_f32 v19, v76, v77
	v_cvt_pk_fp8_f32 v16, v66, v67 op_sel:[0,0,1]
	v_cvt_pk_fp8_f32 v17, v70, v71 op_sel:[0,0,1]
	v_cvt_pk_fp8_f32 v18, v74, v75 op_sel:[0,0,1]
	v_cvt_pk_fp8_f32 v19, v78, v79 op_sel:[0,0,1]
	global_store_dwordx4 v[12:13], v[16:19], off offset:32
	s_waitcnt vmcnt(3)
	v_mul_f32_e32 v80, v0, v80
	v_mul_f32_e32 v81, v0, v81
	v_mul_f32_e32 v82, v0, v82
	v_mul_f32_e32 v83, v0, v83
	v_mul_f32_e32 v84, v0, v84
	v_mul_f32_e32 v85, v0, v85
	v_mul_f32_e32 v86, v0, v86
	v_mul_f32_e32 v87, v0, v87
	v_mul_f32_e32 v88, v0, v88
	v_mul_f32_e32 v89, v0, v89
	v_mul_f32_e32 v90, v0, v90
	v_mul_f32_e32 v91, v0, v91
	v_mul_f32_e32 v92, v0, v92
	v_mul_f32_e32 v93, v0, v93
	v_mul_f32_e32 v94, v0, v94
	v_mul_f32_e32 v95, v0, v95
	v_cvt_pk_fp8_f32 v16, v80, v81
	v_cvt_pk_fp8_f32 v17, v84, v85
	v_cvt_pk_fp8_f32 v18, v88, v89
	v_cvt_pk_fp8_f32 v19, v92, v93
	v_cvt_pk_fp8_f32 v16, v82, v83 op_sel:[0,0,1]
	v_cvt_pk_fp8_f32 v17, v86, v87 op_sel:[0,0,1]
	v_cvt_pk_fp8_f32 v18, v90, v91 op_sel:[0,0,1]
	v_cvt_pk_fp8_f32 v19, v94, v95 op_sel:[0,0,1]
	global_store_dwordx4 v[12:13], v[16:19], off offset:48
	s_and_b64 vcc, exec, s[4:5]
	s_mov_b64 s[4:5], -1
	s_cbranch_vccnz .LBB0_627
	s_andn2_b64 vcc, exec, s[62:63]
	s_cbranch_vccnz .LBB0_626
	s_barrier
	s_branch .LBB0_626
